# additionally the normalized-activation HH stores of the fused epilogue are write-through (sc1)
# baseline (speedup 1.0000x reference)
; __device__ __forceinline__ unsigned cvt_pk_bf16(float lo, float hi) { unsigned r; asm volatile("v_cvt_pk_bf16_f32 %0, %1, %2" : "=v"(r) : "v"(lo), "v"(hi)); return r; }
;     __device__ __forceinline__ void fused(f32x4 (&acc)[2][2][4][2], const Unit& u, int wr, int wc, int fr, int fq, PG8_LAS unsigned char* lds, int wid, int lane) const {
;     ...
;                 for (int m = 0; m < 4; ++m) { const int r = ai * HALF + wr * 64 + m * 16 + fr; const size_t off = (size_t)(u.pm * BM + r) * 1024 + c;
;                     const f32x4 x0 = acc[ai][bj][m][0], x1 = acc[ai][bj][m][1];
;                     if (XF) { *(f32x4*)(XF + off) = x0; *(f32x4*)(XF + off + 4) = x1; }
;                     else { u32x4v w; w.x = cvt_pk_f16(x0[0], x0[1]); w.y = cvt_pk_f16(x0[2], x0[3]); w.z = cvt_pk_f16(x1[0], x1[1]); w.w = cvt_pk_f16(x1[2], x1[3]); *(u32x4v*)(X + off) = w; }
;                     if (HH) { const float rs = S[r]; const f32x4 o0 = x0 * rs * sg[0] + sh[0], o1 = x1 * rs * sg[1] + sh[1];
;                         u32x4v w; w.x = cvt_pk_bf16(o0[0], o0[1]); w.y = cvt_pk_bf16(o0[2], o0[3]); w.z = cvt_pk_bf16(o1[0], o1[1]); w.w = cvt_pk_bf16(o1[2], o1[3]); *(u32x4v*)(HH + off) = w; } }
.LBB0_790:
	s_and_b64 vcc, exec, s[0:1]
	v_lshl_add_u32 v2, v218, 2, 0
	v_lshl_add_u64 v[120:121], v[120:121], 1, s[12:13]
	s_cbranch_vccnz .LBB0_792
	ds_read_b32 v126, v2 offset:4096
	s_waitcnt lgkmcnt(0)
	v_pk_mul_f32 v[96:97], v[96:97], v[126:127] op_sel_hi:[1,0]
	v_pk_mul_f32 v[98:99], v[98:99], v[126:127] op_sel_hi:[1,0]
	v_pk_mul_f32 v[128:129], v[160:161], v[126:127] op_sel_hi:[1,0]
	v_pk_mul_f32 v[126:127], v[162:163], v[126:127] op_sel_hi:[1,0]
	v_pk_fma_f32 v[98:99], v[164:165], v[98:99], v[106:107]
	v_pk_fma_f32 v[96:97], v[142:143], v[96:97], v[104:105]
	v_pk_fma_f32 v[126:127], v[168:169], v[126:127], v[102:103]
	v_pk_fma_f32 v[128:129], v[166:167], v[128:129], v[100:101]
	v_cvt_pk_bf16_f32 v96, v96, v97
	v_cvt_pk_bf16_f32 v97, v98, v99
	s_nop 0
	v_cvt_pk_bf16_f32 v98, v128, v129
	v_cvt_pk_bf16_f32 v99, v126, v127
	flat_store_dwordx4 v[120:121], v[96:99] sc1

; __device__ __forceinline__ unsigned cvt_pk_bf16(float lo, float hi) { unsigned r; asm volatile("v_cvt_pk_bf16_f32 %0, %1, %2" : "=v"(r) : "v"(lo), "v"(hi)); return r; }
;     __device__ __forceinline__ void fused(f32x4 (&acc)[2][2][4][2], const Unit& u, int wr, int wc, int fr, int fq, PG8_LAS unsigned char* lds, int wid, int lane) const {
;     ...
;                 for (int m = 0; m < 4; ++m) { const int r = ai * HALF + wr * 64 + m * 16 + fr; const size_t off = (size_t)(u.pm * BM + r) * 1024 + c;
;                     const f32x4 x0 = acc[ai][bj][m][0], x1 = acc[ai][bj][m][1];
;                     if (XF) { *(f32x4*)(XF + off) = x0; *(f32x4*)(XF + off + 4) = x1; }
;                     else { u32x4v w; w.x = cvt_pk_f16(x0[0], x0[1]); w.y = cvt_pk_f16(x0[2], x0[3]); w.z = cvt_pk_f16(x1[0], x1[1]); w.w = cvt_pk_f16(x1[2], x1[3]); *(u32x4v*)(X + off) = w; }
;                     if (HH) { const float rs = S[r]; const f32x4 o0 = x0 * rs * sg[0] + sh[0], o1 = x1 * rs * sg[1] + sh[1];
;                         u32x4v w; w.x = cvt_pk_bf16(o0[0], o0[1]); w.y = cvt_pk_bf16(o0[2], o0[3]); w.z = cvt_pk_bf16(o1[0], o1[1]); w.w = cvt_pk_bf16(o1[2], o1[3]); *(u32x4v*)(HH + off) = w; } }
.LBB0_795:
	s_and_b64 vcc, exec, s[0:1]
	v_lshl_add_u64 v[96:97], v[96:97], 1, s[12:13]
	s_cbranch_vccnz .LBB0_797
	ds_read_b32 v128, v2 offset:4160
	s_waitcnt lgkmcnt(0)
	v_pk_mul_f32 v[88:89], v[88:89], v[128:129] op_sel_hi:[1,0]
	v_pk_mul_f32 v[90:91], v[90:91], v[128:129] op_sel_hi:[1,0]
	v_pk_mul_f32 v[130:131], v[156:157], v[128:129] op_sel_hi:[1,0]
	v_pk_mul_f32 v[128:129], v[158:159], v[128:129] op_sel_hi:[1,0]
	v_pk_fma_f32 v[90:91], v[164:165], v[90:91], v[106:107]
	v_pk_fma_f32 v[88:89], v[142:143], v[88:89], v[104:105]
	v_pk_fma_f32 v[128:129], v[168:169], v[128:129], v[102:103]
	v_pk_fma_f32 v[130:131], v[166:167], v[130:131], v[100:101]
	v_cvt_pk_bf16_f32 v88, v88, v89
	v_cvt_pk_bf16_f32 v89, v90, v91
	s_nop 0
	v_cvt_pk_bf16_f32 v90, v130, v131
	v_cvt_pk_bf16_f32 v91, v128, v129
	flat_store_dwordx4 v[96:97], v[88:91] sc1

; __device__ __forceinline__ unsigned cvt_pk_bf16(float lo, float hi) { unsigned r; asm volatile("v_cvt_pk_bf16_f32 %0, %1, %2" : "=v"(r) : "v"(lo), "v"(hi)); return r; }
;     __device__ __forceinline__ void fused(f32x4 (&acc)[2][2][4][2], const Unit& u, int wr, int wc, int fr, int fq, PG8_LAS unsigned char* lds, int wid, int lane) const {
;     ...
;                 for (int m = 0; m < 4; ++m) { const int r = ai * HALF + wr * 64 + m * 16 + fr; const size_t off = (size_t)(u.pm * BM + r) * 1024 + c;
;                     const f32x4 x0 = acc[ai][bj][m][0], x1 = acc[ai][bj][m][1];
;                     if (XF) { *(f32x4*)(XF + off) = x0; *(f32x4*)(XF + off + 4) = x1; }
;                     else { u32x4v w; w.x = cvt_pk_f16(x0[0], x0[1]); w.y = cvt_pk_f16(x0[2], x0[3]); w.z = cvt_pk_f16(x1[0], x1[1]); w.w = cvt_pk_f16(x1[2], x1[3]); *(u32x4v*)(X + off) = w; }
;                     if (HH) { const float rs = S[r]; const f32x4 o0 = x0 * rs * sg[0] + sh[0], o1 = x1 * rs * sg[1] + sh[1];
;                         u32x4v w; w.x = cvt_pk_bf16(o0[0], o0[1]); w.y = cvt_pk_bf16(o0[2], o0[3]); w.z = cvt_pk_bf16(o1[0], o1[1]); w.w = cvt_pk_bf16(o1[2], o1[3]); *(u32x4v*)(HH + off) = w; } }
.LBB0_800:
	s_and_b64 vcc, exec, s[0:1]
	v_lshl_add_u64 v[88:89], v[88:89], 1, s[12:13]
	s_cbranch_vccnz .LBB0_802
	ds_read_b32 v90, v2 offset:4224
	s_waitcnt lgkmcnt(0)
	v_pk_mul_f32 v[92:93], v[92:93], v[90:91] op_sel_hi:[1,0]
	v_pk_mul_f32 v[94:95], v[94:95], v[90:91] op_sel_hi:[1,0]
	v_pk_mul_f32 v[132:133], v[152:153], v[90:91] op_sel_hi:[1,0]
	v_pk_mul_f32 v[90:91], v[154:155], v[90:91] op_sel_hi:[1,0]
	v_pk_fma_f32 v[92:93], v[142:143], v[92:93], v[104:105]
	v_pk_fma_f32 v[94:95], v[164:165], v[94:95], v[106:107]
	v_pk_fma_f32 v[134:135], v[168:169], v[90:91], v[102:103]
	v_pk_fma_f32 v[132:133], v[166:167], v[132:133], v[100:101]
	v_cvt_pk_bf16_f32 v90, v92, v93
	v_cvt_pk_bf16_f32 v91, v94, v95
	s_nop 0
	v_cvt_pk_bf16_f32 v92, v132, v133
	v_cvt_pk_bf16_f32 v93, v134, v135
	flat_store_dwordx4 v[88:89], v[90:93] sc1

; __device__ __forceinline__ unsigned cvt_pk_bf16(float lo, float hi) { unsigned r; asm volatile("v_cvt_pk_bf16_f32 %0, %1, %2" : "=v"(r) : "v"(lo), "v"(hi)); return r; }
;     __device__ __forceinline__ void fused(f32x4 (&acc)[2][2][4][2], const Unit& u, int wr, int wc, int fr, int fq, PG8_LAS unsigned char* lds, int wid, int lane) const {
;     ...
;                 for (int m = 0; m < 4; ++m) { const int r = ai * HALF + wr * 64 + m * 16 + fr; const size_t off = (size_t)(u.pm * BM + r) * 1024 + c;
;                     const f32x4 x0 = acc[ai][bj][m][0], x1 = acc[ai][bj][m][1];
;                     if (XF) { *(f32x4*)(XF + off) = x0; *(f32x4*)(XF + off + 4) = x1; }
;                     else { u32x4v w; w.x = cvt_pk_f16(x0[0], x0[1]); w.y = cvt_pk_f16(x0[2], x0[3]); w.z = cvt_pk_f16(x1[0], x1[1]); w.w = cvt_pk_f16(x1[2], x1[3]); *(u32x4v*)(X + off) = w; }
;                     if (HH) { const float rs = S[r]; const f32x4 o0 = x0 * rs * sg[0] + sh[0], o1 = x1 * rs * sg[1] + sh[1];
;                         u32x4v w; w.x = cvt_pk_bf16(o0[0], o0[1]); w.y = cvt_pk_bf16(o0[2], o0[3]); w.z = cvt_pk_bf16(o1[0], o1[1]); w.w = cvt_pk_bf16(o1[2], o1[3]); *(u32x4v*)(HH + off) = w; } }
.LBB0_805:
	s_and_b64 vcc, exec, s[0:1]
	v_lshl_add_u64 v[90:91], v[90:91], 1, s[12:13]
	s_cbranch_vccnz .LBB0_807
	ds_read_b32 v132, v2 offset:4288
	s_waitcnt lgkmcnt(0)
	v_pk_mul_f32 v[72:73], v[72:73], v[132:133] op_sel_hi:[1,0]
	v_pk_mul_f32 v[74:75], v[74:75], v[132:133] op_sel_hi:[1,0]
	v_pk_mul_f32 v[134:135], v[148:149], v[132:133] op_sel_hi:[1,0]
	v_pk_mul_f32 v[132:133], v[150:151], v[132:133] op_sel_hi:[1,0]
	v_pk_fma_f32 v[74:75], v[164:165], v[74:75], v[106:107]
	v_pk_fma_f32 v[72:73], v[142:143], v[72:73], v[104:105]
	v_pk_fma_f32 v[132:133], v[168:169], v[132:133], v[102:103]
	v_pk_fma_f32 v[134:135], v[166:167], v[134:135], v[100:101]
	v_cvt_pk_bf16_f32 v72, v72, v73
	v_cvt_pk_bf16_f32 v73, v74, v75
	s_nop 0
	v_cvt_pk_bf16_f32 v74, v134, v135
	v_cvt_pk_bf16_f32 v75, v132, v133
	flat_store_dwordx4 v[90:91], v[72:75] sc1

; __device__ __forceinline__ unsigned cvt_pk_bf16(float lo, float hi) { unsigned r; asm volatile("v_cvt_pk_bf16_f32 %0, %1, %2" : "=v"(r) : "v"(lo), "v"(hi)); return r; }
;     __device__ __forceinline__ void fused(f32x4 (&acc)[2][2][4][2], const Unit& u, int wr, int wc, int fr, int fq, PG8_LAS unsigned char* lds, int wid, int lane) const {
;     ...
;                 for (int m = 0; m < 4; ++m) { const int r = ai * HALF + wr * 64 + m * 16 + fr; const size_t off = (size_t)(u.pm * BM + r) * 1024 + c;
;                     const f32x4 x0 = acc[ai][bj][m][0], x1 = acc[ai][bj][m][1];
;                     if (XF) { *(f32x4*)(XF + off) = x0; *(f32x4*)(XF + off + 4) = x1; }
;                     else { u32x4v w; w.x = cvt_pk_f16(x0[0], x0[1]); w.y = cvt_pk_f16(x0[2], x0[3]); w.z = cvt_pk_f16(x1[0], x1[1]); w.w = cvt_pk_f16(x1[2], x1[3]); *(u32x4v*)(X + off) = w; }
;                     if (HH) { const float rs = S[r]; const f32x4 o0 = x0 * rs * sg[0] + sh[0], o1 = x1 * rs * sg[1] + sh[1];
;                         u32x4v w; w.x = cvt_pk_bf16(o0[0], o0[1]); w.y = cvt_pk_bf16(o0[2], o0[3]); w.z = cvt_pk_bf16(o1[0], o1[1]); w.w = cvt_pk_bf16(o1[2], o1[3]); *(u32x4v*)(HH + off) = w; } }
.LBB0_810:
	s_and_b64 vcc, exec, s[0:1]
	v_lshl_add_u64 v[72:73], v[72:73], 1, s[12:13]
	s_cbranch_vccnz .LBB0_812
	ds_read_b32 v74, v2 offset:4608
	s_waitcnt lgkmcnt(0)
	v_pk_mul_f32 v[80:81], v[80:81], v[74:75] op_sel_hi:[1,0]
	v_pk_mul_f32 v[82:83], v[82:83], v[74:75] op_sel_hi:[1,0]
	v_pk_mul_f32 v[140:141], v[144:145], v[74:75] op_sel_hi:[1,0]
	v_pk_mul_f32 v[74:75], v[146:147], v[74:75] op_sel_hi:[1,0]
	v_pk_fma_f32 v[82:83], v[164:165], v[82:83], v[106:107]
	v_pk_fma_f32 v[80:81], v[142:143], v[80:81], v[104:105]
	v_pk_fma_f32 v[74:75], v[168:169], v[74:75], v[102:103]
	v_pk_fma_f32 v[140:141], v[166:167], v[140:141], v[100:101]
	v_cvt_pk_bf16_f32 v80, v80, v81
	v_cvt_pk_bf16_f32 v81, v82, v83
	s_nop 0
	v_cvt_pk_bf16_f32 v82, v140, v141
	v_cvt_pk_bf16_f32 v83, v74, v75
	flat_store_dwordx4 v[72:73], v[80:83] sc1

; __device__ __forceinline__ unsigned cvt_pk_bf16(float lo, float hi) { unsigned r; asm volatile("v_cvt_pk_bf16_f32 %0, %1, %2" : "=v"(r) : "v"(lo), "v"(hi)); return r; }
;     __device__ __forceinline__ void fused(f32x4 (&acc)[2][2][4][2], const Unit& u, int wr, int wc, int fr, int fq, PG8_LAS unsigned char* lds, int wid, int lane) const {
;     ...
;                 for (int m = 0; m < 4; ++m) { const int r = ai * HALF + wr * 64 + m * 16 + fr; const size_t off = (size_t)(u.pm * BM + r) * 1024 + c;
;                     const f32x4 x0 = acc[ai][bj][m][0], x1 = acc[ai][bj][m][1];
;                     if (XF) { *(f32x4*)(XF + off) = x0; *(f32x4*)(XF + off + 4) = x1; }
;                     else { u32x4v w; w.x = cvt_pk_f16(x0[0], x0[1]); w.y = cvt_pk_f16(x0[2], x0[3]); w.z = cvt_pk_f16(x1[0], x1[1]); w.w = cvt_pk_f16(x1[2], x1[3]); *(u32x4v*)(X + off) = w; }
;                     if (HH) { const float rs = S[r]; const f32x4 o0 = x0 * rs * sg[0] + sh[0], o1 = x1 * rs * sg[1] + sh[1];
;                         u32x4v w; w.x = cvt_pk_bf16(o0[0], o0[1]); w.y = cvt_pk_bf16(o0[2], o0[3]); w.z = cvt_pk_bf16(o1[0], o1[1]); w.w = cvt_pk_bf16(o1[2], o1[3]); *(u32x4v*)(HH + off) = w; } }
.LBB0_815:
	s_and_b64 vcc, exec, s[0:1]
	v_lshl_add_u64 v[74:75], v[74:75], 1, s[12:13]
	s_cbranch_vccnz .LBB0_817
	ds_read_b32 v80, v2 offset:4672
	s_waitcnt lgkmcnt(0)
	v_pk_mul_f32 v[64:65], v[64:65], v[80:81] op_sel_hi:[1,0]
	v_pk_mul_f32 v[66:67], v[66:67], v[80:81] op_sel_hi:[1,0]
	v_pk_mul_f32 v[136:137], v[136:137], v[80:81] op_sel_hi:[1,0]
	v_pk_mul_f32 v[80:81], v[138:139], v[80:81] op_sel_hi:[1,0]
	v_pk_fma_f32 v[66:67], v[164:165], v[66:67], v[106:107]
	v_pk_fma_f32 v[64:65], v[142:143], v[64:65], v[104:105]
	v_pk_fma_f32 v[80:81], v[168:169], v[80:81], v[102:103]
	v_pk_fma_f32 v[136:137], v[166:167], v[136:137], v[100:101]
	v_cvt_pk_bf16_f32 v64, v64, v65
	v_cvt_pk_bf16_f32 v65, v66, v67
	s_nop 0
	v_cvt_pk_bf16_f32 v66, v136, v137
	v_cvt_pk_bf16_f32 v67, v80, v81
	flat_store_dwordx4 v[74:75], v[64:67] sc1

; __device__ __forceinline__ unsigned cvt_pk_bf16(float lo, float hi) { unsigned r; asm volatile("v_cvt_pk_bf16_f32 %0, %1, %2" : "=v"(r) : "v"(lo), "v"(hi)); return r; }
;     __device__ __forceinline__ void fused(f32x4 (&acc)[2][2][4][2], const Unit& u, int wr, int wc, int fr, int fq, PG8_LAS unsigned char* lds, int wid, int lane) const {
;     ...
;                 for (int m = 0; m < 4; ++m) { const int r = ai * HALF + wr * 64 + m * 16 + fr; const size_t off = (size_t)(u.pm * BM + r) * 1024 + c;
;                     const f32x4 x0 = acc[ai][bj][m][0], x1 = acc[ai][bj][m][1];
;                     if (XF) { *(f32x4*)(XF + off) = x0; *(f32x4*)(XF + off + 4) = x1; }
;                     else { u32x4v w; w.x = cvt_pk_f16(x0[0], x0[1]); w.y = cvt_pk_f16(x0[2], x0[3]); w.z = cvt_pk_f16(x1[0], x1[1]); w.w = cvt_pk_f16(x1[2], x1[3]); *(u32x4v*)(X + off) = w; }
;                     if (HH) { const float rs = S[r]; const f32x4 o0 = x0 * rs * sg[0] + sh[0], o1 = x1 * rs * sg[1] + sh[1];
;                         u32x4v w; w.x = cvt_pk_bf16(o0[0], o0[1]); w.y = cvt_pk_bf16(o0[2], o0[3]); w.z = cvt_pk_bf16(o1[0], o1[1]); w.w = cvt_pk_bf16(o1[2], o1[3]); *(u32x4v*)(HH + off) = w; } }
.LBB0_820:
	s_and_b64 vcc, exec, s[0:1]
	v_lshl_add_u64 v[80:81], v[64:65], 1, s[12:13]
	s_cbranch_vccnz .LBB0_822
	ds_read_b32 v64, v2 offset:4736
	s_waitcnt lgkmcnt(0)
	v_pk_mul_f32 v[66:67], v[68:69], v[64:65] op_sel_hi:[1,0]
	v_pk_mul_f32 v[68:69], v[70:71], v[64:65] op_sel_hi:[1,0]
	v_pk_mul_f32 v[70:71], v[116:117], v[64:65] op_sel_hi:[1,0]
	v_pk_mul_f32 v[64:65], v[118:119], v[64:65] op_sel_hi:[1,0]
	v_pk_fma_f32 v[66:67], v[142:143], v[66:67], v[104:105]
	v_pk_fma_f32 v[68:69], v[164:165], v[68:69], v[106:107]
	v_pk_fma_f32 v[116:117], v[168:169], v[64:65], v[102:103]
	v_pk_fma_f32 v[70:71], v[166:167], v[70:71], v[100:101]
	v_cvt_pk_bf16_f32 v64, v66, v67
	v_cvt_pk_bf16_f32 v65, v68, v69
	s_nop 0
	v_cvt_pk_bf16_f32 v66, v70, v71
	v_cvt_pk_bf16_f32 v67, v116, v117
	flat_store_dwordx4 v[80:81], v[64:67] sc1

; __device__ __forceinline__ unsigned cvt_pk_bf16(float lo, float hi) { unsigned r; asm volatile("v_cvt_pk_bf16_f32 %0, %1, %2" : "=v"(r) : "v"(lo), "v"(hi)); return r; }
;     __device__ __forceinline__ void fused(f32x4 (&acc)[2][2][4][2], const Unit& u, int wr, int wc, int fr, int fq, PG8_LAS unsigned char* lds, int wid, int lane) const {
;     ...
;                 for (int m = 0; m < 4; ++m) { const int r = ai * HALF + wr * 64 + m * 16 + fr; const size_t off = (size_t)(u.pm * BM + r) * 1024 + c;
;                     const f32x4 x0 = acc[ai][bj][m][0], x1 = acc[ai][bj][m][1];
;                     if (XF) { *(f32x4*)(XF + off) = x0; *(f32x4*)(XF + off + 4) = x1; }
;                     else { u32x4v w; w.x = cvt_pk_f16(x0[0], x0[1]); w.y = cvt_pk_f16(x0[2], x0[3]); w.z = cvt_pk_f16(x1[0], x1[1]); w.w = cvt_pk_f16(x1[2], x1[3]); *(u32x4v*)(X + off) = w; }
;                     if (HH) { const float rs = S[r]; const f32x4 o0 = x0 * rs * sg[0] + sh[0], o1 = x1 * rs * sg[1] + sh[1];
;                         u32x4v w; w.x = cvt_pk_bf16(o0[0], o0[1]); w.y = cvt_pk_bf16(o0[2], o0[3]); w.z = cvt_pk_bf16(o1[0], o1[1]); w.w = cvt_pk_bf16(o1[2], o1[3]); *(u32x4v*)(HH + off) = w; } }
.LBB0_825:
	s_and_b64 vcc, exec, s[0:1]
	s_nop 0
	v_lshl_add_u64 v[68:69], v[64:65], 1, s[12:13]
	s_cbranch_vccnz .LBB0_827
	ds_read_b32 v64, v2 offset:4800
	s_waitcnt lgkmcnt(0)
	v_pk_mul_f32 v[52:53], v[52:53], v[64:65] op_sel_hi:[1,0]
	v_pk_mul_f32 v[54:55], v[54:55], v[64:65] op_sel_hi:[1,0]
	v_pk_mul_f32 v[66:67], v[112:113], v[64:65] op_sel_hi:[1,0]
	v_pk_mul_f32 v[64:65], v[114:115], v[64:65] op_sel_hi:[1,0]
	v_pk_fma_f32 v[54:55], v[164:165], v[54:55], v[106:107]
	v_pk_fma_f32 v[52:53], v[142:143], v[52:53], v[104:105]
	v_pk_fma_f32 v[64:65], v[168:169], v[64:65], v[102:103]
	v_pk_fma_f32 v[66:67], v[166:167], v[66:67], v[100:101]
	v_cvt_pk_bf16_f32 v52, v52, v53
	v_cvt_pk_bf16_f32 v53, v54, v55
	s_nop 0
	v_cvt_pk_bf16_f32 v54, v66, v67
	v_cvt_pk_bf16_f32 v55, v64, v65
	flat_store_dwordx4 v[68:69], v[52:55] sc1

; __device__ __forceinline__ unsigned cvt_pk_bf16(float lo, float hi) { unsigned r; asm volatile("v_cvt_pk_bf16_f32 %0, %1, %2" : "=v"(r) : "v"(lo), "v"(hi)); return r; }
;     __device__ __forceinline__ void fused(f32x4 (&acc)[2][2][4][2], const Unit& u, int wr, int wc, int fr, int fq, PG8_LAS unsigned char* lds, int wid, int lane) const {
;     ...
;                 for (int m = 0; m < 4; ++m) { const int r = ai * HALF + wr * 64 + m * 16 + fr; const size_t off = (size_t)(u.pm * BM + r) * 1024 + c;
;                     const f32x4 x0 = acc[ai][bj][m][0], x1 = acc[ai][bj][m][1];
;                     if (XF) { *(f32x4*)(XF + off) = x0; *(f32x4*)(XF + off + 4) = x1; }
;                     else { u32x4v w; w.x = cvt_pk_f16(x0[0], x0[1]); w.y = cvt_pk_f16(x0[2], x0[3]); w.z = cvt_pk_f16(x1[0], x1[1]); w.w = cvt_pk_f16(x1[2], x1[3]); *(u32x4v*)(X + off) = w; }
;                     if (HH) { const float rs = S[r]; const f32x4 o0 = x0 * rs * sg[0] + sh[0], o1 = x1 * rs * sg[1] + sh[1];
;                         u32x4v w; w.x = cvt_pk_bf16(o0[0], o0[1]); w.y = cvt_pk_bf16(o0[2], o0[3]); w.z = cvt_pk_bf16(o1[0], o1[1]); w.w = cvt_pk_bf16(o1[2], o1[3]); *(u32x4v*)(HH + off) = w; } }
.LBB0_834:
	s_and_b64 vcc, exec, s[0:1]
	s_cbranch_vccnz .LBB0_836
	ds_read_b32 v106, v2 offset:4096
	s_waitcnt lgkmcnt(0)
	v_pk_mul_f32 v[32:33], v[32:33], v[106:107] op_sel_hi:[1,0]
	v_pk_mul_f32 v[34:35], v[34:35], v[106:107] op_sel_hi:[1,0]
	v_pk_mul_f32 v[84:85], v[84:85], v[106:107] op_sel_hi:[1,0]
	v_pk_mul_f32 v[86:87], v[86:87], v[106:107] op_sel_hi:[1,0]
	v_pk_fma_f32 v[106:107], v[104:105], v[34:35], v[54:55]
	v_pk_fma_f32 v[34:35], v[102:103], v[32:33], v[52:53]
	v_pk_fma_f32 v[86:87], v[100:101], v[86:87], v[66:67]
	v_pk_fma_f32 v[84:85], v[0:1], v[84:85], v[64:65]
	s_nop 0
	v_cvt_pk_bf16_f32 v32, v84, v85
	v_cvt_pk_bf16_f32 v33, v86, v87
	v_cvt_pk_bf16_f32 v34, v34, v35
	v_cvt_pk_bf16_f32 v35, v106, v107
	flat_store_dwordx4 v[120:121], v[32:35] offset:256 sc1

; __device__ __forceinline__ unsigned cvt_pk_bf16(float lo, float hi) { unsigned r; asm volatile("v_cvt_pk_bf16_f32 %0, %1, %2" : "=v"(r) : "v"(lo), "v"(hi)); return r; }
;     __device__ __forceinline__ void fused(f32x4 (&acc)[2][2][4][2], const Unit& u, int wr, int wc, int fr, int fq, PG8_LAS unsigned char* lds, int wid, int lane) const {
;     ...
;                 for (int m = 0; m < 4; ++m) { const int r = ai * HALF + wr * 64 + m * 16 + fr; const size_t off = (size_t)(u.pm * BM + r) * 1024 + c;
;                     const f32x4 x0 = acc[ai][bj][m][0], x1 = acc[ai][bj][m][1];
;                     if (XF) { *(f32x4*)(XF + off) = x0; *(f32x4*)(XF + off + 4) = x1; }
;                     else { u32x4v w; w.x = cvt_pk_f16(x0[0], x0[1]); w.y = cvt_pk_f16(x0[2], x0[3]); w.z = cvt_pk_f16(x1[0], x1[1]); w.w = cvt_pk_f16(x1[2], x1[3]); *(u32x4v*)(X + off) = w; }
;                     if (HH) { const float rs = S[r]; const f32x4 o0 = x0 * rs * sg[0] + sh[0], o1 = x1 * rs * sg[1] + sh[1];
;                         u32x4v w; w.x = cvt_pk_bf16(o0[0], o0[1]); w.y = cvt_pk_bf16(o0[2], o0[3]); w.z = cvt_pk_bf16(o1[0], o1[1]); w.w = cvt_pk_bf16(o1[2], o1[3]); *(u32x4v*)(HH + off) = w; } }
.LBB0_839:
	s_and_b64 vcc, exec, s[0:1]
	s_cbranch_vccnz .LBB0_841
	ds_read_b32 v32, v2 offset:4160
	s_waitcnt lgkmcnt(0)
	v_pk_mul_f32 v[34:35], v[76:77], v[32:33] op_sel_hi:[1,0]
	v_pk_mul_f32 v[76:77], v[78:79], v[32:33] op_sel_hi:[1,0]
	v_pk_mul_f32 v[28:29], v[28:29], v[32:33] op_sel_hi:[1,0]
	v_pk_mul_f32 v[30:31], v[30:31], v[32:33] op_sel_hi:[1,0]
	v_pk_fma_f32 v[32:33], v[100:101], v[76:77], v[66:67]
	v_pk_fma_f32 v[76:77], v[104:105], v[30:31], v[54:55]
	v_pk_fma_f32 v[30:31], v[102:103], v[28:29], v[52:53]
	v_pk_fma_f32 v[34:35], v[0:1], v[34:35], v[64:65]
	s_nop 0
	v_cvt_pk_bf16_f32 v28, v34, v35
	v_cvt_pk_bf16_f32 v29, v32, v33
	v_cvt_pk_bf16_f32 v30, v30, v31
	v_cvt_pk_bf16_f32 v31, v76, v77
	flat_store_dwordx4 v[96:97], v[28:31] offset:256 sc1

; __device__ __forceinline__ unsigned cvt_pk_bf16(float lo, float hi) { unsigned r; asm volatile("v_cvt_pk_bf16_f32 %0, %1, %2" : "=v"(r) : "v"(lo), "v"(hi)); return r; }
;     __device__ __forceinline__ void fused(f32x4 (&acc)[2][2][4][2], const Unit& u, int wr, int wc, int fr, int fq, PG8_LAS unsigned char* lds, int wid, int lane) const {
;     ...
;                 for (int m = 0; m < 4; ++m) { const int r = ai * HALF + wr * 64 + m * 16 + fr; const size_t off = (size_t)(u.pm * BM + r) * 1024 + c;
;                     const f32x4 x0 = acc[ai][bj][m][0], x1 = acc[ai][bj][m][1];
;                     if (XF) { *(f32x4*)(XF + off) = x0; *(f32x4*)(XF + off + 4) = x1; }
;                     else { u32x4v w; w.x = cvt_pk_f16(x0[0], x0[1]); w.y = cvt_pk_f16(x0[2], x0[3]); w.z = cvt_pk_f16(x1[0], x1[1]); w.w = cvt_pk_f16(x1[2], x1[3]); *(u32x4v*)(X + off) = w; }
;                     if (HH) { const float rs = S[r]; const f32x4 o0 = x0 * rs * sg[0] + sh[0], o1 = x1 * rs * sg[1] + sh[1];
;                         u32x4v w; w.x = cvt_pk_bf16(o0[0], o0[1]); w.y = cvt_pk_bf16(o0[2], o0[3]); w.z = cvt_pk_bf16(o1[0], o1[1]); w.w = cvt_pk_bf16(o1[2], o1[3]); *(u32x4v*)(HH + off) = w; } }
.LBB0_844:
	s_and_b64 vcc, exec, s[0:1]
	s_cbranch_vccnz .LBB0_846
	ds_read_b32 v28, v2 offset:4224
	s_waitcnt lgkmcnt(0)
	v_pk_mul_f32 v[32:33], v[62:63], v[28:29] op_sel_hi:[1,0]
	v_pk_mul_f32 v[24:25], v[24:25], v[28:29] op_sel_hi:[1,0]
	v_pk_mul_f32 v[26:27], v[26:27], v[28:29] op_sel_hi:[1,0]
	v_pk_mul_f32 v[30:31], v[60:61], v[28:29] op_sel_hi:[1,0]
	v_pk_fma_f32 v[28:29], v[100:101], v[32:33], v[66:67]
	v_pk_fma_f32 v[32:33], v[104:105], v[26:27], v[54:55]
	v_pk_fma_f32 v[26:27], v[102:103], v[24:25], v[52:53]
	v_pk_fma_f32 v[30:31], v[0:1], v[30:31], v[64:65]
	s_nop 0
	v_cvt_pk_bf16_f32 v24, v30, v31
	v_cvt_pk_bf16_f32 v25, v28, v29
	v_cvt_pk_bf16_f32 v26, v26, v27
	v_cvt_pk_bf16_f32 v27, v32, v33
	flat_store_dwordx4 v[88:89], v[24:27] offset:256 sc1

; __device__ __forceinline__ unsigned cvt_pk_bf16(float lo, float hi) { unsigned r; asm volatile("v_cvt_pk_bf16_f32 %0, %1, %2" : "=v"(r) : "v"(lo), "v"(hi)); return r; }
;     __device__ __forceinline__ void fused(f32x4 (&acc)[2][2][4][2], const Unit& u, int wr, int wc, int fr, int fq, PG8_LAS unsigned char* lds, int wid, int lane) const {
;     ...
;                 for (int m = 0; m < 4; ++m) { const int r = ai * HALF + wr * 64 + m * 16 + fr; const size_t off = (size_t)(u.pm * BM + r) * 1024 + c;
;                     const f32x4 x0 = acc[ai][bj][m][0], x1 = acc[ai][bj][m][1];
;                     if (XF) { *(f32x4*)(XF + off) = x0; *(f32x4*)(XF + off + 4) = x1; }
;                     else { u32x4v w; w.x = cvt_pk_f16(x0[0], x0[1]); w.y = cvt_pk_f16(x0[2], x0[3]); w.z = cvt_pk_f16(x1[0], x1[1]); w.w = cvt_pk_f16(x1[2], x1[3]); *(u32x4v*)(X + off) = w; }
;                     if (HH) { const float rs = S[r]; const f32x4 o0 = x0 * rs * sg[0] + sh[0], o1 = x1 * rs * sg[1] + sh[1];
;                         u32x4v w; w.x = cvt_pk_bf16(o0[0], o0[1]); w.y = cvt_pk_bf16(o0[2], o0[3]); w.z = cvt_pk_bf16(o1[0], o1[1]); w.w = cvt_pk_bf16(o1[2], o1[3]); *(u32x4v*)(HH + off) = w; } }
.LBB0_849:
	s_and_b64 vcc, exec, s[0:1]
	s_cbranch_vccnz .LBB0_851
	ds_read_b32 v24, v2 offset:4288
	s_waitcnt lgkmcnt(0)
	v_pk_mul_f32 v[28:29], v[58:59], v[24:25] op_sel_hi:[1,0]
	v_pk_mul_f32 v[20:21], v[20:21], v[24:25] op_sel_hi:[1,0]
	v_pk_mul_f32 v[22:23], v[22:23], v[24:25] op_sel_hi:[1,0]
	v_pk_mul_f32 v[26:27], v[56:57], v[24:25] op_sel_hi:[1,0]
	v_pk_fma_f32 v[24:25], v[100:101], v[28:29], v[66:67]
	v_pk_fma_f32 v[28:29], v[104:105], v[22:23], v[54:55]
	v_pk_fma_f32 v[22:23], v[102:103], v[20:21], v[52:53]
	v_pk_fma_f32 v[26:27], v[0:1], v[26:27], v[64:65]
	s_nop 0
	v_cvt_pk_bf16_f32 v20, v26, v27
	v_cvt_pk_bf16_f32 v21, v24, v25
	v_cvt_pk_bf16_f32 v22, v22, v23
	v_cvt_pk_bf16_f32 v23, v28, v29
	flat_store_dwordx4 v[90:91], v[20:23] offset:256 sc1

; __device__ __forceinline__ unsigned cvt_pk_bf16(float lo, float hi) { unsigned r; asm volatile("v_cvt_pk_bf16_f32 %0, %1, %2" : "=v"(r) : "v"(lo), "v"(hi)); return r; }
;     __device__ __forceinline__ void fused(f32x4 (&acc)[2][2][4][2], const Unit& u, int wr, int wc, int fr, int fq, PG8_LAS unsigned char* lds, int wid, int lane) const {
;     ...
;                 for (int m = 0; m < 4; ++m) { const int r = ai * HALF + wr * 64 + m * 16 + fr; const size_t off = (size_t)(u.pm * BM + r) * 1024 + c;
;                     const f32x4 x0 = acc[ai][bj][m][0], x1 = acc[ai][bj][m][1];
;                     if (XF) { *(f32x4*)(XF + off) = x0; *(f32x4*)(XF + off + 4) = x1; }
;                     else { u32x4v w; w.x = cvt_pk_f16(x0[0], x0[1]); w.y = cvt_pk_f16(x0[2], x0[3]); w.z = cvt_pk_f16(x1[0], x1[1]); w.w = cvt_pk_f16(x1[2], x1[3]); *(u32x4v*)(X + off) = w; }
;                     if (HH) { const float rs = S[r]; const f32x4 o0 = x0 * rs * sg[0] + sh[0], o1 = x1 * rs * sg[1] + sh[1];
;                         u32x4v w; w.x = cvt_pk_bf16(o0[0], o0[1]); w.y = cvt_pk_bf16(o0[2], o0[3]); w.z = cvt_pk_bf16(o1[0], o1[1]); w.w = cvt_pk_bf16(o1[2], o1[3]); *(u32x4v*)(HH + off) = w; } }
.LBB0_854:
	s_and_b64 vcc, exec, s[0:1]
	s_cbranch_vccnz .LBB0_856
	ds_read_b32 v20, v2 offset:4608
	s_waitcnt lgkmcnt(0)
	v_pk_mul_f32 v[24:25], v[50:51], v[20:21] op_sel_hi:[1,0]
	v_pk_mul_f32 v[16:17], v[16:17], v[20:21] op_sel_hi:[1,0]
	v_pk_mul_f32 v[18:19], v[18:19], v[20:21] op_sel_hi:[1,0]
	v_pk_mul_f32 v[22:23], v[48:49], v[20:21] op_sel_hi:[1,0]
	v_pk_fma_f32 v[20:21], v[100:101], v[24:25], v[66:67]
	v_pk_fma_f32 v[24:25], v[104:105], v[18:19], v[54:55]
	v_pk_fma_f32 v[18:19], v[102:103], v[16:17], v[52:53]
	v_pk_fma_f32 v[22:23], v[0:1], v[22:23], v[64:65]
	s_nop 0
	v_cvt_pk_bf16_f32 v16, v22, v23
	v_cvt_pk_bf16_f32 v17, v20, v21
	v_cvt_pk_bf16_f32 v18, v18, v19
	v_cvt_pk_bf16_f32 v19, v24, v25
	flat_store_dwordx4 v[72:73], v[16:19] offset:256 sc1

; __device__ __forceinline__ unsigned cvt_pk_bf16(float lo, float hi) { unsigned r; asm volatile("v_cvt_pk_bf16_f32 %0, %1, %2" : "=v"(r) : "v"(lo), "v"(hi)); return r; }
;     __device__ __forceinline__ void fused(f32x4 (&acc)[2][2][4][2], const Unit& u, int wr, int wc, int fr, int fq, PG8_LAS unsigned char* lds, int wid, int lane) const {
;     ...
;                 for (int m = 0; m < 4; ++m) { const int r = ai * HALF + wr * 64 + m * 16 + fr; const size_t off = (size_t)(u.pm * BM + r) * 1024 + c;
;                     const f32x4 x0 = acc[ai][bj][m][0], x1 = acc[ai][bj][m][1];
;                     if (XF) { *(f32x4*)(XF + off) = x0; *(f32x4*)(XF + off + 4) = x1; }
;                     else { u32x4v w; w.x = cvt_pk_f16(x0[0], x0[1]); w.y = cvt_pk_f16(x0[2], x0[3]); w.z = cvt_pk_f16(x1[0], x1[1]); w.w = cvt_pk_f16(x1[2], x1[3]); *(u32x4v*)(X + off) = w; }
;                     if (HH) { const float rs = S[r]; const f32x4 o0 = x0 * rs * sg[0] + sh[0], o1 = x1 * rs * sg[1] + sh[1];
;                         u32x4v w; w.x = cvt_pk_bf16(o0[0], o0[1]); w.y = cvt_pk_bf16(o0[2], o0[3]); w.z = cvt_pk_bf16(o1[0], o1[1]); w.w = cvt_pk_bf16(o1[2], o1[3]); *(u32x4v*)(HH + off) = w; } }
.LBB0_859:
	s_and_b64 vcc, exec, s[0:1]
	s_cbranch_vccnz .LBB0_861
	ds_read_b32 v16, v2 offset:4672
	s_waitcnt lgkmcnt(0)
	v_pk_mul_f32 v[20:21], v[46:47], v[16:17] op_sel_hi:[1,0]
	v_pk_mul_f32 v[12:13], v[12:13], v[16:17] op_sel_hi:[1,0]
	v_pk_mul_f32 v[14:15], v[14:15], v[16:17] op_sel_hi:[1,0]
	v_pk_mul_f32 v[18:19], v[44:45], v[16:17] op_sel_hi:[1,0]
	v_pk_fma_f32 v[16:17], v[100:101], v[20:21], v[66:67]
	v_pk_fma_f32 v[20:21], v[104:105], v[14:15], v[54:55]
	v_pk_fma_f32 v[14:15], v[102:103], v[12:13], v[52:53]
	v_pk_fma_f32 v[18:19], v[0:1], v[18:19], v[64:65]
	s_nop 0
	v_cvt_pk_bf16_f32 v12, v18, v19
	v_cvt_pk_bf16_f32 v13, v16, v17
	v_cvt_pk_bf16_f32 v14, v14, v15
	v_cvt_pk_bf16_f32 v15, v20, v21
	flat_store_dwordx4 v[74:75], v[12:15] offset:256 sc1

; __device__ __forceinline__ unsigned cvt_pk_bf16(float lo, float hi) { unsigned r; asm volatile("v_cvt_pk_bf16_f32 %0, %1, %2" : "=v"(r) : "v"(lo), "v"(hi)); return r; }
;     __device__ __forceinline__ void fused(f32x4 (&acc)[2][2][4][2], const Unit& u, int wr, int wc, int fr, int fq, PG8_LAS unsigned char* lds, int wid, int lane) const {
;     ...
;                 for (int m = 0; m < 4; ++m) { const int r = ai * HALF + wr * 64 + m * 16 + fr; const size_t off = (size_t)(u.pm * BM + r) * 1024 + c;
;                     const f32x4 x0 = acc[ai][bj][m][0], x1 = acc[ai][bj][m][1];
;                     if (XF) { *(f32x4*)(XF + off) = x0; *(f32x4*)(XF + off + 4) = x1; }
;                     else { u32x4v w; w.x = cvt_pk_f16(x0[0], x0[1]); w.y = cvt_pk_f16(x0[2], x0[3]); w.z = cvt_pk_f16(x1[0], x1[1]); w.w = cvt_pk_f16(x1[2], x1[3]); *(u32x4v*)(X + off) = w; }
;                     if (HH) { const float rs = S[r]; const f32x4 o0 = x0 * rs * sg[0] + sh[0], o1 = x1 * rs * sg[1] + sh[1];
;                         u32x4v w; w.x = cvt_pk_bf16(o0[0], o0[1]); w.y = cvt_pk_bf16(o0[2], o0[3]); w.z = cvt_pk_bf16(o1[0], o1[1]); w.w = cvt_pk_bf16(o1[2], o1[3]); *(u32x4v*)(HH + off) = w; } }
.LBB0_864:
	s_and_b64 vcc, exec, s[0:1]
	s_cbranch_vccnz .LBB0_866
	ds_read_b32 v12, v2 offset:4736
	s_waitcnt lgkmcnt(0)
	v_pk_mul_f32 v[16:17], v[42:43], v[12:13] op_sel_hi:[1,0]
	v_pk_mul_f32 v[8:9], v[8:9], v[12:13] op_sel_hi:[1,0]
	v_pk_mul_f32 v[10:11], v[10:11], v[12:13] op_sel_hi:[1,0]
	v_pk_mul_f32 v[14:15], v[40:41], v[12:13] op_sel_hi:[1,0]
	v_pk_fma_f32 v[12:13], v[100:101], v[16:17], v[66:67]
	v_pk_fma_f32 v[16:17], v[104:105], v[10:11], v[54:55]
	v_pk_fma_f32 v[10:11], v[102:103], v[8:9], v[52:53]
	v_pk_fma_f32 v[14:15], v[0:1], v[14:15], v[64:65]
	s_nop 0
	v_cvt_pk_bf16_f32 v8, v14, v15
	v_cvt_pk_bf16_f32 v9, v12, v13
	v_cvt_pk_bf16_f32 v10, v10, v11
	v_cvt_pk_bf16_f32 v11, v16, v17
	flat_store_dwordx4 v[80:81], v[8:11] offset:256 sc1

; __device__ __forceinline__ unsigned cvt_pk_bf16(float lo, float hi) { unsigned r; asm volatile("v_cvt_pk_bf16_f32 %0, %1, %2" : "=v"(r) : "v"(lo), "v"(hi)); return r; }
;     __device__ __forceinline__ void fused(f32x4 (&acc)[2][2][4][2], const Unit& u, int wr, int wc, int fr, int fq, PG8_LAS unsigned char* lds, int wid, int lane) const {
;     ...
;                 for (int m = 0; m < 4; ++m) { const int r = ai * HALF + wr * 64 + m * 16 + fr; const size_t off = (size_t)(u.pm * BM + r) * 1024 + c;
;                     const f32x4 x0 = acc[ai][bj][m][0], x1 = acc[ai][bj][m][1];
;                     if (XF) { *(f32x4*)(XF + off) = x0; *(f32x4*)(XF + off + 4) = x1; }
;                     else { u32x4v w; w.x = cvt_pk_f16(x0[0], x0[1]); w.y = cvt_pk_f16(x0[2], x0[3]); w.z = cvt_pk_f16(x1[0], x1[1]); w.w = cvt_pk_f16(x1[2], x1[3]); *(u32x4v*)(X + off) = w; }
;                     if (HH) { const float rs = S[r]; const f32x4 o0 = x0 * rs * sg[0] + sh[0], o1 = x1 * rs * sg[1] + sh[1];
;                         u32x4v w; w.x = cvt_pk_bf16(o0[0], o0[1]); w.y = cvt_pk_bf16(o0[2], o0[3]); w.z = cvt_pk_bf16(o1[0], o1[1]); w.w = cvt_pk_bf16(o1[2], o1[3]); *(u32x4v*)(HH + off) = w; } }
.LBB0_869:
	s_and_b64 vcc, exec, s[0:1]
	s_cbranch_vccnz .LBB0_871
	ds_read_b32 v2, v2 offset:4800
	s_waitcnt lgkmcnt(0)
	v_pk_mul_f32 v[8:9], v[36:37], v[2:3] op_sel_hi:[1,0]
	v_pk_mul_f32 v[4:5], v[4:5], v[2:3] op_sel_hi:[1,0]
	v_pk_mul_f32 v[6:7], v[6:7], v[2:3] op_sel_hi:[1,0]
	v_pk_mul_f32 v[10:11], v[38:39], v[2:3] op_sel_hi:[1,0]
	v_pk_fma_f32 v[0:1], v[0:1], v[8:9], v[64:65]
	v_pk_fma_f32 v[8:9], v[104:105], v[6:7], v[54:55]
	v_pk_fma_f32 v[6:7], v[102:103], v[4:5], v[52:53]
	v_pk_fma_f32 v[10:11], v[100:101], v[10:11], v[66:67]
	v_cvt_pk_bf16_f32 v4, v0, v1
	s_nop 0
	v_cvt_pk_bf16_f32 v5, v10, v11
	v_cvt_pk_bf16_f32 v6, v6, v7
	v_cvt_pk_bf16_f32 v7, v8, v9
	flat_store_dwordx4 v[68:69], v[4:7] offset:256 sc1
